# nt policy also on out-projection residual loads and norm-phase xbuf loads
# speedup vs baseline: 1.0155x; 1.0038x over previous
.LBB0_804:
	s_cmp_lt_i32 s57, 24
	s_movk_i32 s0, 0x3000
	s_cselect_b32 s0, s0, 0x6000
	s_cmp_gt_i32 s57, 15
	s_cselect_b32 s0, s0, 0
	s_lshl_b32 s0, s0, 2
	s_add_u32 s0, s36, s0
	v_mov_b32_e32 v146, v180
	s_addc_u32 s24, s37, 0
	s_lshl_b64 s[20:21], s[2:3], 2
	s_add_u32 s3, s0, s20
	v_readfirstlane_b32 s17, v146
	s_addc_u32 s25, s24, s21
	s_lshr_b32 s0, s17, 1
	s_and_b32 s34, s0, 0x60
	s_lshl_b32 s0, s34, 2
	v_lshrrev_b32_e32 v32, 2, v146
	s_add_u32 s24, s3, s0
	v_and_b32_e32 v147, 12, v32
	s_addc_u32 s25, s25, 0
	v_lshlrev_b32_e32 v144, 2, v147
	v_lshl_add_u64 v[32:33], s[24:25], 0, v[144:145]
	s_mov_b64 s[24:25], 0x8000
	s_mov_b32 s3, 0x8000
	v_lshl_add_u64 v[34:35], v[32:33], 0, s[24:25]
	v_add_co_u32_e32 v32, vcc, s3, v32
	s_ashr_i32 s3, s17, 2
	s_andn2_b32 s3, s3, 63
	v_and_or_b32 v146, v146, 15, s16
	v_readlane_b32 s60, v254, 28
	v_addc_co_u32_e32 v33, vcc, 0, v33, vcc
	v_add_u32_e32 v146, s3, v146
	v_readlane_b32 s61, v254, 29
	v_readlane_b32 s62, v254, 30
	v_readlane_b32 s63, v254, 31
	v_or_b32_e32 v147, s2, v147
	s_mov_b64 s[2:3], s[60:61]
	s_mov_b64 s[16:17], s[62:63]
	v_add_u32_e32 v149, 0xfffff000, v146
	v_cmp_gt_i32_e32 vcc, s55, v146
	global_load_dwordx4 v[40:43], v[34:35], off offset:64
	global_load_dwordx4 v[36:39], v[34:35], off offset:512
	global_load_dwordx4 v[52:55], v[32:33], off
	s_nop 0
	global_load_dwordx4 v[32:35], v[34:35], off offset:576
	v_or_b32_e32 v178, s34, v147
	v_ashrrev_i32_e32 v147, 31, v146
	v_cndmask_b32_e32 v150, v149, v146, vcc
	v_mov_b32_e32 v149, s17
	v_mov_b32_e32 v152, s3
	v_cndmask_b32_e32 v151, 0, v147, vcc
	v_cndmask_b32_e32 v153, v149, v152, vcc
	v_mov_b32_e32 v149, s16
	v_mov_b32_e32 v152, s2
	v_cndmask_b32_e32 v152, v149, v152, vcc
	v_lshlrev_b64 v[150:151], 14, v[150:151]
	v_lshl_add_u64 v[150:151], v[152:153], 0, v[150:151]
	v_lshl_add_u64 v[150:151], v[150:151], 0, s[20:21]
	v_lshl_add_u64 v[150:151], v[150:151], 0, s[0:1]
	v_lshl_add_u64 v[162:163], v[150:151], 0, v[144:145]
	flat_load_dwordx4 v[150:153], v[162:163] nt
	flat_load_dwordx4 v[154:157], v[162:163] offset:64 nt
	flat_load_dwordx4 v[158:161], v[162:163] offset:512 nt
	s_nop 0
	flat_load_dwordx4 v[162:165], v[162:163] offset:576 nt
	v_or_b32_e32 v218, 16, v146
	s_mov_b64 s[2:3], s[60:61]
	s_mov_b64 s[16:17], s[62:63]
	v_add_u32_e32 v149, 0xfffff010, v146
	v_cmp_gt_i32_e32 vcc, s55, v218
	v_ashrrev_i32_e32 v219, 31, v218
	v_mov_b32_e32 v168, s3
	v_cndmask_b32_e32 v166, v149, v218, vcc
	v_mov_b32_e32 v149, s17
	v_cndmask_b32_e32 v167, 0, v219, vcc
	v_cndmask_b32_e32 v169, v149, v168, vcc
	v_mov_b32_e32 v149, s16
	v_mov_b32_e32 v168, s2
	v_cndmask_b32_e32 v168, v149, v168, vcc
	v_lshlrev_b64 v[166:167], 14, v[166:167]
	v_lshl_add_u64 v[166:167], v[168:169], 0, v[166:167]
	v_lshl_add_u64 v[166:167], v[166:167], 0, s[20:21]
	v_lshl_add_u64 v[166:167], v[166:167], 0, s[0:1]
	v_lshl_add_u64 v[182:183], v[166:167], 0, v[144:145]
	flat_load_dwordx4 v[166:169], v[182:183] nt
	flat_load_dwordx4 v[170:173], v[182:183] offset:64 nt
	flat_load_dwordx4 v[174:177], v[182:183] offset:512 nt
	s_nop 0
	flat_load_dwordx4 v[182:185], v[182:183] offset:576 nt
	v_or_b32_e32 v220, 32, v146
	s_mov_b64 s[2:3], s[60:61]
	s_mov_b64 s[16:17], s[62:63]
	v_add_u32_e32 v149, 0xfffff020, v146
	v_cmp_gt_i32_e32 vcc, s55, v220
	v_ashrrev_i32_e32 v221, 31, v220
	v_mov_b32_e32 v179, s3
	v_cndmask_b32_e32 v186, v149, v220, vcc
	v_mov_b32_e32 v149, s17
	v_cndmask_b32_e32 v187, 0, v221, vcc
	v_cndmask_b32_e32 v189, v149, v179, vcc
	v_mov_b32_e32 v149, s16
	v_mov_b32_e32 v179, s2
	v_cndmask_b32_e32 v188, v149, v179, vcc
	v_lshlrev_b64 v[186:187], 14, v[186:187]
	v_lshl_add_u64 v[186:187], v[188:189], 0, v[186:187]
	v_lshl_add_u64 v[186:187], v[186:187], 0, s[20:21]
	v_lshl_add_u64 v[186:187], v[186:187], 0, s[0:1]
	v_lshl_add_u64 v[198:199], v[186:187], 0, v[144:145]
	flat_load_dwordx4 v[186:189], v[198:199] nt
	flat_load_dwordx4 v[190:193], v[198:199] offset:64 nt
	flat_load_dwordx4 v[194:197], v[198:199] offset:512 nt
	s_nop 0
	flat_load_dwordx4 v[198:201], v[198:199] offset:576 nt
	v_or_b32_e32 v222, 48, v146
	s_mov_b64 s[2:3], s[60:61]
	s_mov_b64 s[16:17], s[62:63]
	v_add_u32_e32 v149, 0xfffff030, v146
	v_cmp_gt_i32_e32 vcc, s55, v222
	v_ashrrev_i32_e32 v223, 31, v222
	v_mov_b32_e32 v179, s3
	v_cndmask_b32_e32 v202, v149, v222, vcc
	v_mov_b32_e32 v149, s17
	v_cndmask_b32_e32 v203, 0, v223, vcc
	v_cndmask_b32_e32 v205, v149, v179, vcc
	v_mov_b32_e32 v149, s16
	v_mov_b32_e32 v179, s2
	v_cndmask_b32_e32 v204, v149, v179, vcc
	v_lshlrev_b64 v[202:203], 14, v[202:203]
	v_lshl_add_u64 v[202:203], v[204:205], 0, v[202:203]
	v_lshl_add_u64 v[202:203], v[202:203], 0, s[20:21]
	v_lshl_add_u64 v[202:203], v[202:203], 0, s[0:1]
	v_lshl_add_u64 v[214:215], v[202:203], 0, v[144:145]
	flat_load_dwordx4 v[202:205], v[214:215] nt
	flat_load_dwordx4 v[206:209], v[214:215] offset:64 nt
	flat_load_dwordx4 v[210:213], v[214:215] offset:512 nt
	s_nop 0
	flat_load_dwordx4 v[214:217], v[214:215] offset:576 nt
	v_lshlrev_b64 v[224:225], 13, v[146:147]
	v_ashrrev_i32_e32 v179, 31, v178
	v_lshlrev_b64 v[222:223], 13, v[222:223]
	s_mov_b64 s[2:3], s[60:61]
	s_mov_b64 s[16:17], s[62:63]
	s_add_i32 s56, s56, s94
	s_cmpk_lt_i32 s56, 0x200
	v_readlane_b32 s64, v254, 32
	v_readlane_b32 s65, v254, 33
	v_readlane_b32 s66, v254, 34
	s_waitcnt vmcnt(0) lgkmcnt(0)
	v_fma_f32 v136, v136, v52, v150
	v_fma_f32 v137, v137, v53, v151
	v_cvt_pk_bf16_f32 v150, v136, v137
	v_fma_f32 v136, v138, v54, v152
	v_fmac_f32_e32 v153, v139, v55
	v_cvt_pk_bf16_f32 v151, v136, v153
	v_lshl_add_u64 v[138:139], s[50:51], 0, v[224:225]
	v_lshlrev_b64 v[136:137], 1, v[178:179]
	v_lshl_add_u64 v[138:139], v[138:139], 0, v[136:137]
	v_fma_f32 v128, v128, v40, v154
	v_fma_f32 v129, v129, v41, v155
	global_store_dwordx2 v[138:139], v[150:151], off
	v_cvt_pk_bf16_f32 v128, v128, v129
	v_fma_f32 v129, v130, v42, v156
	v_fmac_f32_e32 v157, v131, v43
	v_cvt_pk_bf16_f32 v129, v129, v157
	global_store_dwordx2 v[138:139], v[128:129], off offset:32
	v_fma_f32 v128, v140, v36, v158
	v_fma_f32 v129, v141, v37, v159
	v_cvt_pk_bf16_f32 v128, v128, v129
	v_fma_f32 v129, v142, v38, v160
	v_fmac_f32_e32 v161, v143, v39
	v_cvt_pk_bf16_f32 v129, v129, v161
	global_store_dwordx2 v[138:139], v[128:129], off offset:256
	v_fma_f32 v128, v132, v32, v162
	v_fma_f32 v129, v133, v33, v163
	v_cvt_pk_bf16_f32 v128, v128, v129
	v_fma_f32 v129, v134, v34, v164
	v_fmac_f32_e32 v165, v135, v35
	v_cvt_pk_bf16_f32 v129, v129, v165
	global_store_dwordx2 v[138:139], v[128:129], off offset:288
	v_lshlrev_b64 v[128:129], 13, v[218:219]
	v_fma_f32 v120, v120, v52, v166
	v_fma_f32 v121, v121, v53, v167
	v_cvt_pk_bf16_f32 v120, v120, v121
	v_fma_f32 v121, v122, v54, v168
	v_fmac_f32_e32 v169, v123, v55
	v_lshl_add_u64 v[122:123], s[50:51], 0, v[128:129]
	v_lshl_add_u64 v[122:123], v[122:123], 0, v[136:137]
	v_fma_f32 v112, v112, v40, v170
	v_fma_f32 v113, v113, v41, v171
	v_cvt_pk_bf16_f32 v121, v121, v169
	global_store_dwordx2 v[122:123], v[120:121], off
	v_cvt_pk_bf16_f32 v112, v112, v113
	v_fma_f32 v113, v114, v42, v172
	v_fmac_f32_e32 v173, v115, v43
	v_cvt_pk_bf16_f32 v113, v113, v173
	global_store_dwordx2 v[122:123], v[112:113], off offset:32
	v_fma_f32 v112, v124, v36, v174
	v_fma_f32 v113, v125, v37, v175
	v_cvt_pk_bf16_f32 v112, v112, v113
	v_fma_f32 v113, v126, v38, v176
	v_fmac_f32_e32 v177, v127, v39
	v_cvt_pk_bf16_f32 v113, v113, v177
	global_store_dwordx2 v[122:123], v[112:113], off offset:256
	v_fma_f32 v112, v116, v32, v182
	v_fma_f32 v113, v117, v33, v183
	v_cvt_pk_bf16_f32 v112, v112, v113
	v_fma_f32 v113, v118, v34, v184
	v_fmac_f32_e32 v185, v119, v35
	v_cvt_pk_bf16_f32 v113, v113, v185
	global_store_dwordx2 v[122:123], v[112:113], off offset:288
	v_lshlrev_b64 v[112:113], 13, v[220:221]
	v_fma_f32 v104, v104, v52, v186
	v_fma_f32 v105, v105, v53, v187
	v_cvt_pk_bf16_f32 v104, v104, v105
	v_fma_f32 v105, v106, v54, v188
	v_fmac_f32_e32 v189, v107, v55
	v_lshl_add_u64 v[106:107], s[50:51], 0, v[112:113]
	v_lshl_add_u64 v[106:107], v[106:107], 0, v[136:137]
	v_fma_f32 v96, v96, v40, v190
	v_fma_f32 v97, v97, v41, v191
	v_cvt_pk_bf16_f32 v105, v105, v189
	global_store_dwordx2 v[106:107], v[104:105], off
	v_cvt_pk_bf16_f32 v96, v96, v97
	v_fma_f32 v97, v98, v42, v192
	v_fmac_f32_e32 v193, v99, v43
	v_cvt_pk_bf16_f32 v97, v97, v193
	global_store_dwordx2 v[106:107], v[96:97], off offset:32
	v_fma_f32 v96, v108, v36, v194
	v_fma_f32 v97, v109, v37, v195
	v_cvt_pk_bf16_f32 v96, v96, v97
	v_fma_f32 v97, v110, v38, v196
	v_fmac_f32_e32 v197, v111, v39
	v_cvt_pk_bf16_f32 v97, v97, v197
	global_store_dwordx2 v[106:107], v[96:97], off offset:256
	v_fma_f32 v96, v100, v32, v198
	v_fma_f32 v97, v101, v33, v199
	v_cvt_pk_bf16_f32 v96, v96, v97
	v_fma_f32 v97, v102, v34, v200
	v_fma_f32 v88, v88, v52, v202
	v_fma_f32 v89, v89, v53, v203
	v_fmac_f32_e32 v201, v103, v35
	v_cvt_pk_bf16_f32 v97, v97, v201
	global_store_dwordx2 v[106:107], v[96:97], off offset:288
	v_cvt_pk_bf16_f32 v88, v88, v89
	v_fma_f32 v89, v90, v54, v204
	v_fmac_f32_e32 v205, v91, v55
	v_lshl_add_u64 v[90:91], s[50:51], 0, v[222:223]
	v_lshl_add_u64 v[90:91], v[90:91], 0, v[136:137]
	v_fma_f32 v80, v80, v40, v206
	v_fma_f32 v81, v81, v41, v207
	v_cvt_pk_bf16_f32 v89, v89, v205
	global_store_dwordx2 v[90:91], v[88:89], off
	v_cvt_pk_bf16_f32 v80, v80, v81
	v_fma_f32 v81, v82, v42, v208
	v_fmac_f32_e32 v209, v83, v43
	v_cvt_pk_bf16_f32 v81, v81, v209
	global_store_dwordx2 v[90:91], v[80:81], off offset:32
	v_fma_f32 v80, v92, v36, v210
	v_fma_f32 v81, v93, v37, v211
	v_cvt_pk_bf16_f32 v80, v80, v81
	v_fma_f32 v81, v94, v38, v212
	v_fmac_f32_e32 v213, v95, v39
	v_cvt_pk_bf16_f32 v81, v81, v213
	global_store_dwordx2 v[90:91], v[80:81], off offset:256
	v_fma_f32 v80, v84, v32, v214
	v_fma_f32 v81, v85, v33, v215
	v_cvt_pk_bf16_f32 v80, v80, v81
	v_fma_f32 v81, v86, v34, v216
	v_add_u32_e32 v142, 0x80, v146
	v_fmac_f32_e32 v217, v87, v35
	v_cvt_pk_bf16_f32 v81, v81, v217
	global_store_dwordx2 v[90:91], v[80:81], off offset:288
	v_add_u32_e32 v80, 0xfffff080, v146
	v_ashrrev_i32_e32 v143, 31, v142
	v_cmp_gt_i32_e32 vcc, s55, v142
	v_mov_b32_e32 v82, s17
	v_mov_b32_e32 v83, s3
	v_cndmask_b32_e32 v81, 0, v143, vcc
	v_cndmask_b32_e32 v80, v80, v142, vcc
	v_cndmask_b32_e32 v83, v82, v83, vcc
	v_mov_b32_e32 v82, s16
	v_mov_b32_e32 v84, s2
	v_cndmask_b32_e32 v82, v82, v84, vcc
	v_lshlrev_b64 v[80:81], 14, v[80:81]
	v_lshl_add_u64 v[80:81], v[82:83], 0, v[80:81]
	v_lshl_add_u64 v[80:81], v[80:81], 0, s[20:21]
	v_lshl_add_u64 v[80:81], v[80:81], 0, s[0:1]
	v_lshl_add_u64 v[92:93], v[80:81], 0, v[144:145]
	flat_load_dwordx4 v[80:83], v[92:93] nt
	flat_load_dwordx4 v[84:87], v[92:93] offset:64 nt
	flat_load_dwordx4 v[88:91], v[92:93] offset:512 nt
	s_nop 0
	flat_load_dwordx4 v[92:95], v[92:93] offset:576 nt
	v_add_u32_e32 v154, 0x90, v146
	s_mov_b64 s[2:3], s[60:61]
	s_mov_b64 s[16:17], s[62:63]
	v_add_u32_e32 v96, 0xfffff090, v146
	v_ashrrev_i32_e32 v155, 31, v154
	v_cmp_gt_i32_e32 vcc, s55, v154
	v_mov_b32_e32 v98, s17
	v_mov_b32_e32 v99, s3
	v_cndmask_b32_e32 v97, 0, v155, vcc
	v_cndmask_b32_e32 v96, v96, v154, vcc
	v_cndmask_b32_e32 v99, v98, v99, vcc
	v_mov_b32_e32 v98, s16
	v_mov_b32_e32 v100, s2
	v_cndmask_b32_e32 v98, v98, v100, vcc
	v_lshlrev_b64 v[96:97], 14, v[96:97]
	v_lshl_add_u64 v[96:97], v[98:99], 0, v[96:97]
	v_lshl_add_u64 v[96:97], v[96:97], 0, s[20:21]
	v_lshl_add_u64 v[96:97], v[96:97], 0, s[0:1]
	v_lshl_add_u64 v[108:109], v[96:97], 0, v[144:145]
	flat_load_dwordx4 v[96:99], v[108:109] nt
	flat_load_dwordx4 v[100:103], v[108:109] offset:64 nt
	flat_load_dwordx4 v[104:107], v[108:109] offset:512 nt
	s_nop 0
	flat_load_dwordx4 v[108:111], v[108:109] offset:576 nt
	v_add_u32_e32 v156, 0xa0, v146
	s_mov_b64 s[2:3], s[60:61]
	s_mov_b64 s[16:17], s[62:63]
	v_add_u32_e32 v112, 0xfffff0a0, v146
	v_ashrrev_i32_e32 v157, 31, v156
	v_cmp_gt_i32_e32 vcc, s55, v156
	v_mov_b32_e32 v114, s17
	v_mov_b32_e32 v115, s3
	v_cndmask_b32_e32 v113, 0, v157, vcc
	v_cndmask_b32_e32 v112, v112, v156, vcc
	v_cndmask_b32_e32 v115, v114, v115, vcc
	v_mov_b32_e32 v114, s16
	v_mov_b32_e32 v116, s2
	v_cndmask_b32_e32 v114, v114, v116, vcc
	v_lshlrev_b64 v[112:113], 14, v[112:113]
	v_lshl_add_u64 v[112:113], v[114:115], 0, v[112:113]
	v_lshl_add_u64 v[112:113], v[112:113], 0, s[20:21]
	v_lshl_add_u64 v[112:113], v[112:113], 0, s[0:1]
	v_lshl_add_u64 v[124:125], v[112:113], 0, v[144:145]
	v_add_u32_e32 v158, 0xb0, v146
	s_mov_b64 s[2:3], s[60:61]
	s_mov_b64 s[16:17], s[62:63]
	flat_load_dwordx4 v[112:115], v[124:125] nt
	flat_load_dwordx4 v[116:119], v[124:125] offset:64 nt
	flat_load_dwordx4 v[120:123], v[124:125] offset:512 nt
	s_nop 0
	flat_load_dwordx4 v[124:127], v[124:125] offset:576 nt
	v_add_u32_e32 v128, 0xfffff0b0, v146
	v_ashrrev_i32_e32 v159, 31, v158
	v_cmp_gt_i32_e32 vcc, s55, v158
	v_mov_b32_e32 v130, s17
	v_mov_b32_e32 v131, s3
	v_cndmask_b32_e32 v129, 0, v159, vcc
	v_cndmask_b32_e32 v128, v128, v158, vcc
	v_cndmask_b32_e32 v131, v130, v131, vcc
	v_mov_b32_e32 v130, s16
	v_mov_b32_e32 v132, s2
	v_cndmask_b32_e32 v130, v130, v132, vcc
	v_lshlrev_b64 v[128:129], 14, v[128:129]
	v_lshl_add_u64 v[128:129], v[130:131], 0, v[128:129]
	v_lshl_add_u64 v[128:129], v[128:129], 0, s[20:21]
	v_lshl_add_u64 v[128:129], v[128:129], 0, s[0:1]
	v_lshl_add_u64 v[146:147], v[128:129], 0, v[144:145]
	flat_load_dwordx4 v[128:131], v[146:147] nt
	flat_load_dwordx4 v[132:135], v[146:147] offset:64 nt
	flat_load_dwordx4 v[138:141], v[146:147] offset:512 nt
	flat_load_dwordx4 v[150:153], v[146:147] offset:576 nt
	v_lshlrev_b64 v[142:143], 13, v[142:143]
	v_lshlrev_b64 v[146:147], 13, v[158:159]
	v_readlane_b32 s67, v254, 35
	v_readlane_b32 s68, v254, 36
	v_readlane_b32 s69, v254, 37
	v_readlane_b32 s70, v254, 38
	v_readlane_b32 s71, v254, 39
	v_readlane_b32 s72, v254, 40
	v_readlane_b32 s73, v254, 41
	v_readlane_b32 s74, v254, 42
	s_waitcnt vmcnt(0) lgkmcnt(0)
	v_fma_f32 v76, v76, v52, v80
	v_fma_f32 v77, v77, v53, v81
	v_cvt_pk_bf16_f32 v76, v76, v77
	v_fma_f32 v77, v78, v54, v82
	v_fmac_f32_e32 v83, v79, v55
	v_lshl_add_u64 v[78:79], s[50:51], 0, v[142:143]
	v_lshl_add_u64 v[78:79], v[78:79], 0, v[136:137]
	v_fma_f32 v68, v68, v40, v84
	v_fma_f32 v69, v69, v41, v85
	v_cvt_pk_bf16_f32 v77, v77, v83
	global_store_dwordx2 v[78:79], v[76:77], off
	v_cvt_pk_bf16_f32 v68, v68, v69
	v_fma_f32 v69, v70, v42, v86
	v_fmac_f32_e32 v87, v71, v43
	v_cvt_pk_bf16_f32 v69, v69, v87
	global_store_dwordx2 v[78:79], v[68:69], off offset:32
	v_fma_f32 v68, v72, v36, v88
	v_fma_f32 v69, v73, v37, v89
	v_cvt_pk_bf16_f32 v68, v68, v69
	v_fma_f32 v69, v74, v38, v90
	v_fma_f32 v64, v64, v32, v92
	v_fma_f32 v65, v65, v33, v93
	v_fmac_f32_e32 v91, v75, v39
	v_cvt_pk_bf16_f32 v69, v69, v91
	global_store_dwordx2 v[78:79], v[68:69], off offset:256
	v_cvt_pk_bf16_f32 v64, v64, v65
	v_fma_f32 v65, v66, v34, v94
	v_fmac_f32_e32 v95, v67, v35
	v_cvt_pk_bf16_f32 v65, v65, v95
	global_store_dwordx2 v[78:79], v[64:65], off offset:288
	v_lshlrev_b64 v[64:65], 13, v[154:155]
	v_fma_f32 v60, v60, v52, v96
	v_fma_f32 v61, v61, v53, v97
	v_cvt_pk_bf16_f32 v60, v60, v61
	v_fma_f32 v61, v62, v54, v98
	v_fmac_f32_e32 v99, v63, v55
	v_lshl_add_u64 v[62:63], s[50:51], 0, v[64:65]
	v_lshl_add_u64 v[62:63], v[62:63], 0, v[136:137]
	v_fma_f32 v48, v48, v40, v100
	v_fma_f32 v49, v49, v41, v101
	v_cvt_pk_bf16_f32 v61, v61, v99
	global_store_dwordx2 v[62:63], v[60:61], off
	v_cvt_pk_bf16_f32 v48, v48, v49
	v_fma_f32 v49, v50, v42, v102
	v_fmac_f32_e32 v103, v51, v43
	v_cvt_pk_bf16_f32 v49, v49, v103
	global_store_dwordx2 v[62:63], v[48:49], off offset:32
	v_fma_f32 v48, v56, v36, v104
	v_fma_f32 v49, v57, v37, v105
	v_cvt_pk_bf16_f32 v48, v48, v49
	v_fma_f32 v49, v58, v38, v106
	v_fma_f32 v44, v44, v32, v108
	v_fma_f32 v45, v45, v33, v109
	v_fmac_f32_e32 v107, v59, v39
	v_cvt_pk_bf16_f32 v49, v49, v107
	global_store_dwordx2 v[62:63], v[48:49], off offset:256
	v_cvt_pk_bf16_f32 v44, v44, v45
	v_fma_f32 v45, v46, v34, v110
	v_fmac_f32_e32 v111, v47, v35
	v_cvt_pk_bf16_f32 v45, v45, v111
	global_store_dwordx2 v[62:63], v[44:45], off offset:288
	v_lshlrev_b64 v[44:45], 13, v[156:157]
	v_fma_f32 v28, v28, v52, v112
	v_fma_f32 v29, v29, v53, v113
	v_cvt_pk_bf16_f32 v28, v28, v29
	v_fma_f32 v29, v30, v54, v114
	v_fmac_f32_e32 v115, v31, v55
	v_lshl_add_u64 v[30:31], s[50:51], 0, v[44:45]
	v_lshl_add_u64 v[30:31], v[30:31], 0, v[136:137]
	v_fma_f32 v20, v20, v40, v116
	v_fma_f32 v21, v21, v41, v117
	v_cvt_pk_bf16_f32 v29, v29, v115
	global_store_dwordx2 v[30:31], v[28:29], off
	v_cvt_pk_bf16_f32 v20, v20, v21
	v_fma_f32 v21, v22, v42, v118
	v_fmac_f32_e32 v119, v23, v43
	v_cvt_pk_bf16_f32 v21, v21, v119
	global_store_dwordx2 v[30:31], v[20:21], off offset:32
	v_fma_f32 v20, v24, v36, v120
	v_fma_f32 v21, v25, v37, v121
	v_cvt_pk_bf16_f32 v20, v20, v21
	v_fma_f32 v21, v26, v38, v122
	v_fma_f32 v16, v16, v32, v124
	v_fma_f32 v17, v17, v33, v125
	v_fmac_f32_e32 v123, v27, v39
	v_cvt_pk_bf16_f32 v21, v21, v123
	global_store_dwordx2 v[30:31], v[20:21], off offset:256
	v_cvt_pk_bf16_f32 v16, v16, v17
	v_fma_f32 v17, v18, v34, v126
	v_fma_f32 v12, v12, v52, v128
	v_fma_f32 v13, v13, v53, v129
	v_fmac_f32_e32 v127, v19, v35
	v_cvt_pk_bf16_f32 v17, v17, v127
	global_store_dwordx2 v[30:31], v[16:17], off offset:288
	v_cvt_pk_bf16_f32 v12, v12, v13
	v_fma_f32 v13, v14, v54, v130
	v_fmac_f32_e32 v131, v15, v55
	v_lshl_add_u64 v[14:15], s[50:51], 0, v[146:147]
	v_lshl_add_u64 v[14:15], v[14:15], 0, v[136:137]
	v_fma_f32 v4, v4, v40, v132
	v_fma_f32 v5, v5, v41, v133
	v_cvt_pk_bf16_f32 v13, v13, v131
	global_store_dwordx2 v[14:15], v[12:13], off
	v_cvt_pk_bf16_f32 v4, v4, v5
	v_fma_f32 v5, v6, v42, v134
	v_fmac_f32_e32 v135, v7, v43
	v_cvt_pk_bf16_f32 v5, v5, v135
	global_store_dwordx2 v[14:15], v[4:5], off offset:32
	v_fma_f32 v4, v8, v36, v138
	v_fma_f32 v5, v9, v37, v139
	v_cvt_pk_bf16_f32 v4, v4, v5
	v_fma_f32 v5, v10, v38, v140
	v_fma_f32 v0, v0, v32, v150
	v_fma_f32 v1, v1, v33, v151
	v_fmac_f32_e32 v141, v11, v39
	v_cvt_pk_bf16_f32 v5, v5, v141
	global_store_dwordx2 v[14:15], v[4:5], off offset:256
	v_cvt_pk_bf16_f32 v0, v0, v1
	v_fma_f32 v1, v2, v34, v152
	v_readlane_b32 s75, v254, 43
	v_fmac_f32_e32 v153, v3, v35
	v_cvt_pk_bf16_f32 v1, v1, v153
	global_store_dwordx2 v[14:15], v[0:1], off offset:288
	s_barrier
	s_cbranch_scc0 .LBB0_815

.LBB0_873:
	s_or_b64 exec, exec, s[2:3]
	v_and_b32_e32 v5, 63, v0
	v_ashrrev_i32_e32 v0, 4, v0
	v_and_b32_e32 v7, -4, v0
	v_lshlrev_b32_e32 v0, 4, v5
	v_cmp_lt_i32_e32 vcc, v43, v42
	v_lshl_add_u64 v[2:3], s[50:51], 0, v[0:1]
	v_lshlrev_b32_e32 v4, 3, v5
	v_cndmask_b32_e32 v0, v41, v43, vcc
	v_cmp_lt_i32_e32 vcc, v44, v42
	v_lshlrev_b32_e32 v49, 2, v0
	v_or_b32_e32 v8, 0x804, v4
	v_cndmask_b32_e32 v0, v41, v44, vcc
	v_cmp_lt_i32_e32 vcc, v45, v42
	v_lshlrev_b32_e32 v50, 2, v0
	v_or_b32_e32 v12, 0xa04, v4
	v_cndmask_b32_e32 v0, v41, v45, vcc
	v_cmp_lt_i32_e32 vcc, v46, v42
	v_lshlrev_b32_e32 v51, 2, v0
	v_or_b32_e32 v14, 0xc04, v4
	v_cndmask_b32_e32 v0, v41, v46, vcc
	v_cmp_lt_i32_e32 vcc, v47, v42
	v_lshlrev_b32_e32 v52, 2, v0
	v_or_b32_e32 v18, 0xe04, v4
	v_cndmask_b32_e32 v0, v41, v47, vcc
	v_cmp_lt_i32_e32 vcc, v48, v42
	v_or_b32_e32 v6, 0x800, v4
	v_or_b32_e32 v10, 0xa00, v4
	v_or_b32_e32 v16, 0xc00, v4
	v_or_b32_e32 v20, 0xe00, v4
	v_lshlrev_b32_e32 v53, 2, v0
	v_cndmask_b32_e32 v0, v41, v48, vcc
	v_readlane_b32 s52, v254, 12
	s_mov_b32 s2, 0
	v_lshlrev_b32_e32 v54, 2, v0
	v_lshl_add_u32 v55, v5, 5, 0
	v_add_u32_e32 v56, s10, v7
	v_lshlrev_b32_e32 v4, 1, v4
	v_lshlrev_b32_e32 v6, 1, v6
	v_lshlrev_b32_e32 v8, 1, v8
	v_lshlrev_b32_e32 v10, 1, v10
	v_lshlrev_b32_e32 v0, 1, v12
	v_lshlrev_b32_e32 v12, 1, v16
	v_lshlrev_b32_e32 v14, 1, v14
	v_lshlrev_b32_e32 v16, 1, v20
	v_mov_b32_e32 v17, v1
	v_lshlrev_b32_e32 v18, 1, v18
	v_mov_b32_e32 v19, v1
	v_mov_b32_e32 v5, v1
	v_mov_b32_e32 v7, v1
	v_mov_b32_e32 v9, v1
	v_mov_b32_e32 v11, v1
	v_readlane_b32 s56, v254, 16
	v_readlane_b32 s57, v254, 17
	s_waitcnt lgkmcnt(0)
	s_barrier
	v_readlane_b32 s53, v254, 13
	v_readlane_b32 s54, v254, 14
	v_readlane_b32 s55, v254, 15
	v_readlane_b32 s58, v254, 18
	v_readlane_b32 s59, v254, 19
	v_readlane_b32 s60, v254, 20
	v_readlane_b32 s61, v254, 21
	v_readlane_b32 s62, v254, 22
	v_readlane_b32 s63, v254, 23
	v_readlane_b32 s64, v254, 24
	v_readlane_b32 s65, v254, 25
	v_readlane_b32 s66, v254, 26
	v_readlane_b32 s67, v254, 27
	s_mov_b64 s[32:33], 0x1000
	s_mov_b64 s[34:35], 0x2000
	v_mov_b32_e32 v136, v56
	v_ashrrev_i32_e32 v137, 31, v56
	v_lshlrev_b64 v[136:137], 13, v[136:137]
	v_lshl_add_u64 v[250:251], v[2:3], 0, v[136:137]
	global_load_dwordx4 v[186:189], v[250:251], off nt
	global_load_dwordx4 v[190:193], v[250:251], off offset:1024 nt
	global_load_dwordx4 v[194:197], v[250:251], off offset:2048 nt
	global_load_dwordx4 v[198:201], v[250:251], off offset:3072 nt
	v_lshl_add_u64 v[136:137], v[250:251], 0, s[32:33]
	global_load_dwordx4 v[202:205], v[136:137], off offset:3072 nt
	global_load_dwordx4 v[206:209], v[136:137], off nt
	global_load_dwordx4 v[210:213], v[136:137], off offset:1024 nt
	global_load_dwordx4 v[214:217], v[136:137], off offset:2048 nt
	s_waitcnt vmcnt(0)
.LBB0_874:
	v_add_u32_e32 v20, s2, v56
	v_ashrrev_i32_e32 v21, 31, v20
	v_lshlrev_b64 v[36:37], 13, v[20:21]
	v_lshl_add_u64 v[24:25], v[2:3], 0, v[36:37]
	v_mov_b32_e32 v20, v186
	v_mov_b32_e32 v21, v187
	v_mov_b32_e32 v22, v188
	v_mov_b32_e32 v23, v189
	s_movk_i32 s3, 0x1000
	v_lshl_add_u64 v[36:37], s[56:57], 0, v[36:37]
	s_add_i32 s2, s2, 1
	s_cmp_eq_u32 s2, 4
	s_nop 0
	v_lshlrev_b32_e32 v101, 16, v20
	v_and_b32_e32 v100, 0xffff0000, v20
	v_lshlrev_b32_e32 v99, 16, v21
	v_and_b32_e32 v98, 0xffff0000, v21
	v_lshlrev_b32_e32 v97, 16, v22
	v_and_b32_e32 v96, 0xffff0000, v22
	v_lshlrev_b32_e32 v95, 16, v23
	v_and_b32_e32 v94, 0xffff0000, v23
	v_mov_b32_e32 v20, v190
	v_mov_b32_e32 v21, v191
	v_mov_b32_e32 v22, v192
	v_mov_b32_e32 v23, v193
	s_nop 0
	v_lshlrev_b32_e32 v93, 16, v20
	v_and_b32_e32 v92, 0xffff0000, v20
	v_lshlrev_b32_e32 v91, 16, v21
	v_and_b32_e32 v90, 0xffff0000, v21
	v_lshlrev_b32_e32 v88, 16, v22
	v_and_b32_e32 v86, 0xffff0000, v22
	v_lshlrev_b32_e32 v84, 16, v23
	v_and_b32_e32 v82, 0xffff0000, v23
	v_mov_b32_e32 v20, v194
	v_mov_b32_e32 v21, v195
	v_mov_b32_e32 v22, v196
	v_mov_b32_e32 v23, v197
	s_nop 0
	v_lshlrev_b32_e32 v81, 16, v20
	v_and_b32_e32 v80, 0xffff0000, v20
	v_lshlrev_b32_e32 v77, 16, v21
	v_and_b32_e32 v76, 0xffff0000, v21
	v_lshlrev_b32_e32 v73, 16, v22
	v_and_b32_e32 v72, 0xffff0000, v22
	v_lshlrev_b32_e32 v69, 16, v23
	v_and_b32_e32 v68, 0xffff0000, v23
	v_mov_b32_e32 v20, v198
	v_mov_b32_e32 v21, v199
	v_mov_b32_e32 v22, v200
	v_mov_b32_e32 v23, v201
	v_add_co_u32_e32 v24, vcc, s3, v24
	s_mov_b32 s3, 0x800000
	s_nop 0
	v_addc_co_u32_e32 v25, vcc, 0, v25, vcc
	v_mov_b32_e32 v102, v202
	v_mov_b32_e32 v103, v203
	v_mov_b32_e32 v104, v204
	v_mov_b32_e32 v105, v205
	s_nop 0
	v_lshlrev_b32_e32 v65, 16, v20
	v_and_b32_e32 v64, 0xffff0000, v20
	v_lshlrev_b32_e32 v63, 16, v21
	v_and_b32_e32 v61, 0xffff0000, v21
	v_lshlrev_b32_e32 v39, 16, v22
	v_and_b32_e32 v38, 0xffff0000, v22
	v_lshlrev_b32_e32 v15, 16, v23
	v_and_b32_e32 v13, 0xffff0000, v23
	v_mov_b32_e32 v20, v206
	v_mov_b32_e32 v21, v207
	v_mov_b32_e32 v22, v208
	v_mov_b32_e32 v23, v209
	s_nop 0
	v_lshlrev_b32_e32 v27, 16, v104
	s_nop 0
	v_lshlrev_b32_e32 v89, 16, v20
	v_and_b32_e32 v87, 0xffff0000, v20
	v_lshlrev_b32_e32 v85, 16, v21
	v_and_b32_e32 v83, 0xffff0000, v21
	v_lshlrev_b32_e32 v79, 16, v22
	v_and_b32_e32 v78, 0xffff0000, v22
	v_lshlrev_b32_e32 v75, 16, v23
	v_and_b32_e32 v74, 0xffff0000, v23
	v_mov_b32_e32 v20, v210
	v_mov_b32_e32 v21, v211
	v_mov_b32_e32 v22, v212
	v_mov_b32_e32 v23, v213
	s_nop 0
	v_lshlrev_b32_e32 v71, 16, v20
	v_and_b32_e32 v70, 0xffff0000, v20
	v_lshlrev_b32_e32 v67, 16, v21
	v_and_b32_e32 v66, 0xffff0000, v21
	v_mul_f32_e32 v20, v100, v100
	v_mul_f32_e32 v21, v96, v96
	v_fmac_f32_e32 v20, v101, v101
	v_fmac_f32_e32 v21, v97, v97
	v_fmac_f32_e32 v20, v99, v99
	v_fmac_f32_e32 v21, v95, v95
	v_fmac_f32_e32 v20, v98, v98
	v_fmac_f32_e32 v21, v94, v94
	v_add_f32_e32 v20, v20, v21
	v_mul_f32_e32 v21, v92, v92
	v_fmac_f32_e32 v21, v93, v93
	v_fmac_f32_e32 v21, v91, v91
	v_fmac_f32_e32 v21, v90, v90
	v_add_f32_e32 v20, v20, v21
	v_mul_f32_e32 v21, v86, v86
	v_fmac_f32_e32 v21, v88, v88
	v_fmac_f32_e32 v21, v84, v84
	v_fmac_f32_e32 v21, v82, v82
	v_add_f32_e32 v20, v20, v21
	v_mul_f32_e32 v21, v80, v80
	v_fmac_f32_e32 v21, v81, v81
	v_fmac_f32_e32 v21, v77, v77
	v_fmac_f32_e32 v21, v76, v76
	v_add_f32_e32 v20, v20, v21
	v_mul_f32_e32 v21, v72, v72
	v_fmac_f32_e32 v21, v73, v73
	v_fmac_f32_e32 v21, v69, v69
	v_fmac_f32_e32 v21, v68, v68
	v_add_f32_e32 v20, v20, v21
	v_mul_f32_e32 v21, v64, v64
	v_fmac_f32_e32 v21, v65, v65
	v_fmac_f32_e32 v21, v63, v63
	v_fmac_f32_e32 v21, v61, v61
	v_add_f32_e32 v20, v20, v21
	v_mul_f32_e32 v21, v38, v38
	v_fmac_f32_e32 v21, v39, v39
	v_fmac_f32_e32 v21, v15, v15
	v_fmac_f32_e32 v21, v13, v13
	v_add_f32_e32 v20, v20, v21
	v_mul_f32_e32 v21, v87, v87
	v_fmac_f32_e32 v21, v89, v89
	v_fmac_f32_e32 v21, v85, v85
	v_fmac_f32_e32 v21, v83, v83
	v_add_f32_e32 v20, v20, v21
	v_mul_f32_e32 v21, v78, v78
	v_fmac_f32_e32 v21, v79, v79
	v_fmac_f32_e32 v21, v75, v75
	v_fmac_f32_e32 v21, v74, v74
	v_add_f32_e32 v20, v20, v21
	v_mul_f32_e32 v21, v70, v70
	v_fmac_f32_e32 v21, v71, v71
	v_fmac_f32_e32 v21, v67, v67
	v_and_b32_e32 v60, 0xffff0000, v22
	v_fmac_f32_e32 v21, v66, v66
	v_lshlrev_b32_e32 v62, 16, v22
	v_add_f32_e32 v20, v20, v21
	v_mul_f32_e32 v21, v60, v60
	v_lshlrev_b32_e32 v59, 16, v23
	v_fmac_f32_e32 v21, v62, v62
	v_and_b32_e32 v58, 0xffff0000, v23
	v_fmac_f32_e32 v21, v59, v59
	v_fmac_f32_e32 v21, v58, v58
	v_add_f32_e32 v26, v20, v21
	v_mov_b32_e32 v20, v214
	v_mov_b32_e32 v21, v215
	v_mov_b32_e32 v22, v216
	v_mov_b32_e32 v23, v217
	s_cbranch_scc1 .Lnorm1_nopf
	v_lshl_add_u64 v[250:251], v[250:251], 0, s[34:35]
	global_load_dwordx4 v[186:189], v[250:251], off nt
	global_load_dwordx4 v[190:193], v[250:251], off offset:1024 nt
	global_load_dwordx4 v[194:197], v[250:251], off offset:2048 nt
	global_load_dwordx4 v[198:201], v[250:251], off offset:3072 nt
	v_lshl_add_u64 v[136:137], v[250:251], 0, s[32:33]
	global_load_dwordx4 v[202:205], v[136:137], off offset:3072 nt
	global_load_dwordx4 v[206:209], v[136:137], off nt
	global_load_dwordx4 v[210:213], v[136:137], off offset:1024 nt
	global_load_dwordx4 v[214:217], v[136:137], off offset:2048 nt

.LBB0_1515:
	s_cmp_lt_i32 s45, 24
	s_cselect_b32 s17, 0xc000, s43
	s_cmp_gt_i32 s45, 15
	s_cselect_b32 s17, s17, 0x9000
	s_lshl_b32 s17, s17, 2
	s_add_u32 s17, s36, s17
	v_mov_b32_e32 v66, v180
	s_addc_u32 s28, s37, 0
	s_lshl_b64 s[26:27], s[2:3], 2
	s_add_u32 s17, s17, s26
	v_readfirstlane_b32 s0, v66
	s_addc_u32 s27, s28, s27
	s_lshr_b32 s26, s0, 1
	s_and_b32 s28, s26, 0x60
	s_lshl_b32 s26, s28, 2
	s_add_u32 s26, s17, s26
	s_addc_u32 s27, s27, 0
	s_ashr_i32 s0, s0, 2
	v_lshrrev_b32_e32 v64, 2, v66
	s_andn2_b32 s0, s0, 63
	v_and_or_b32 v66, v66, 15, s16
	v_add_u32_e32 v146, s0, v66
	v_ashrrev_i32_e32 v147, 31, v146
	v_lshlrev_b64 v[66:67], 13, v[146:147]
	v_and_b32_e32 v70, 12, v64
	v_lshl_add_u64 v[152:153], s[50:51], 0, v[66:67]
	s_lshl_b64 s[16:17], s[2:3], 1
	v_lshlrev_b32_e32 v144, 2, v70
	v_lshl_add_u64 v[66:67], v[152:153], 0, s[16:17]
	s_lshl_b32 s0, s28, 1
	v_lshl_add_u64 v[64:65], s[26:27], 0, v[144:145]
	v_lshl_add_u64 v[66:67], v[66:67], 0, s[0:1]
	v_lshlrev_b32_e32 v144, 1, v70
	v_lshl_add_u64 v[66:67], v[66:67], 0, v[144:145]
	global_load_dwordx2 v[154:155], v[66:67], off nt
	global_load_dwordx2 v[156:157], v[66:67], off offset:32 nt
	global_load_dwordx2 v[158:159], v[66:67], off offset:256 nt
	global_load_dwordx2 v[160:161], v[66:67], off offset:288 nt
	v_or_b32_e32 v66, 16, v146
	v_ashrrev_i32_e32 v67, 31, v66
	v_lshlrev_b64 v[66:67], 13, v[66:67]
	v_lshl_add_u64 v[162:163], s[50:51], 0, v[66:67]
	v_lshl_add_u64 v[66:67], v[162:163], 0, s[16:17]
	v_lshl_add_u64 v[66:67], v[66:67], 0, s[0:1]
	v_lshl_add_u64 v[66:67], v[66:67], 0, v[144:145]
	global_load_dwordx2 v[164:165], v[66:67], off nt
	global_load_dwordx2 v[166:167], v[66:67], off offset:32 nt
	global_load_dwordx2 v[168:169], v[66:67], off offset:256 nt
	global_load_dwordx2 v[170:171], v[66:67], off offset:288 nt
	v_or_b32_e32 v66, 32, v146
	v_ashrrev_i32_e32 v67, 31, v66
	v_lshlrev_b64 v[66:67], 13, v[66:67]
	v_lshl_add_u64 v[172:173], s[50:51], 0, v[66:67]
	v_or_b32_e32 v68, 48, v146
	v_lshl_add_u64 v[66:67], v[172:173], 0, s[16:17]
	v_ashrrev_i32_e32 v69, 31, v68
	v_lshl_add_u64 v[66:67], v[66:67], 0, s[0:1]
	v_lshlrev_b64 v[68:69], 13, v[68:69]
	v_lshl_add_u64 v[66:67], v[66:67], 0, v[144:145]
	v_lshl_add_u64 v[148:149], s[50:51], 0, v[68:69]
	global_load_dwordx2 v[174:175], v[66:67], off nt
	global_load_dwordx2 v[176:177], v[66:67], off offset:32 nt
	global_load_dwordx2 v[178:179], v[66:67], off offset:256 nt
	global_load_dwordx2 v[182:183], v[66:67], off offset:288 nt
	v_lshl_add_u64 v[66:67], v[148:149], 0, s[16:17]
	v_lshl_add_u64 v[66:67], v[66:67], 0, s[0:1]
	v_lshl_add_u64 v[66:67], v[66:67], 0, v[144:145]
	global_load_dwordx2 v[184:185], v[66:67], off nt
	global_load_dwordx2 v[186:187], v[66:67], off offset:32 nt
	global_load_dwordx2 v[188:189], v[66:67], off offset:256 nt
	global_load_dwordx2 v[190:191], v[66:67], off offset:288 nt
	v_add_co_u32_e32 v66, vcc, s40, v64
	s_add_i32 s44, s44, s94
	s_nop 0
	v_addc_co_u32_e32 v67, vcc, 0, v65, vcc
	global_load_dwordx4 v[76:79], v[66:67], off
	v_lshl_add_u64 v[64:65], v[64:65], 0, s[24:25]
	global_load_dwordx4 v[72:75], v[64:65], off offset:64
	v_or_b32_e32 v66, s2, v70
	v_or_b32_e32 v192, s28, v66
	global_load_dwordx4 v[68:71], v[64:65], off offset:512
	s_nop 0
	global_load_dwordx4 v[64:67], v[64:65], off offset:576
	s_cmpk_lt_i32 s44, 0x200
	s_waitcnt vmcnt(0)
	v_lshlrev_b32_e32 v193, 16, v155
	v_and_b32_e32 v155, 0xffff0000, v155
	v_lshlrev_b32_e32 v147, 16, v154
	v_and_b32_e32 v151, 0xffff0000, v154
	v_lshlrev_b32_e32 v194, 16, v156
	v_and_b32_e32 v156, 0xffff0000, v156
	v_lshlrev_b32_e32 v195, 16, v157
	v_and_b32_e32 v157, 0xffff0000, v157
	v_lshlrev_b32_e32 v196, 16, v158
	v_and_b32_e32 v158, 0xffff0000, v158
	v_lshlrev_b32_e32 v197, 16, v159
	v_and_b32_e32 v159, 0xffff0000, v159
	v_lshlrev_b32_e32 v201, 16, v165
	v_and_b32_e32 v165, 0xffff0000, v165
	v_lshlrev_b32_e32 v198, 16, v160
	v_and_b32_e32 v160, 0xffff0000, v160
	v_lshlrev_b32_e32 v199, 16, v161
	v_and_b32_e32 v161, 0xffff0000, v161
	v_lshlrev_b32_e32 v200, 16, v164
	v_and_b32_e32 v164, 0xffff0000, v164
	v_lshlrev_b32_e32 v202, 16, v166
	v_and_b32_e32 v166, 0xffff0000, v166
	v_lshlrev_b32_e32 v203, 16, v167
	v_and_b32_e32 v167, 0xffff0000, v167
	v_lshlrev_b32_e32 v204, 16, v168
	v_and_b32_e32 v168, 0xffff0000, v168
	v_lshlrev_b32_e32 v205, 16, v169
	v_and_b32_e32 v169, 0xffff0000, v169
	v_lshlrev_b32_e32 v209, 16, v175
	v_and_b32_e32 v175, 0xffff0000, v175
	v_lshlrev_b32_e32 v206, 16, v170
	v_and_b32_e32 v170, 0xffff0000, v170
	v_lshlrev_b32_e32 v207, 16, v171
	v_and_b32_e32 v171, 0xffff0000, v171
	v_lshlrev_b32_e32 v208, 16, v174
	v_fmac_f32_e32 v193, v142, v78
	v_fmac_f32_e32 v155, v143, v79
	v_fmac_f32_e32 v147, v140, v76
	v_fmac_f32_e32 v151, v141, v77
	v_cvt_pk_bf16_f32 v154, v147, v151
	v_cvt_pk_bf16_f32 v155, v193, v155
	v_ashrrev_i32_e32 v193, 31, v192
	v_lshlrev_b64 v[140:141], 1, v[192:193]
	v_lshl_add_u64 v[142:143], v[152:153], 0, v[140:141]
	global_store_dwordx2 v[142:143], v[154:155], off
	v_fmac_f32_e32 v194, v128, v72
	v_fmac_f32_e32 v156, v129, v73
	v_cvt_pk_bf16_f32 v128, v194, v156
	v_fmac_f32_e32 v195, v130, v74
	v_fmac_f32_e32 v157, v131, v75
	v_cvt_pk_bf16_f32 v129, v195, v157
	global_store_dwordx2 v[142:143], v[128:129], off offset:32
	v_fmac_f32_e32 v196, v136, v68
	v_fmac_f32_e32 v158, v137, v69
	v_cvt_pk_bf16_f32 v128, v196, v158
	v_fmac_f32_e32 v197, v138, v70
	v_fmac_f32_e32 v159, v139, v71
	v_cvt_pk_bf16_f32 v129, v197, v159
	v_fmac_f32_e32 v201, v126, v78
	v_fmac_f32_e32 v165, v127, v79
	v_lshl_add_u64 v[126:127], v[162:163], 0, v[140:141]
	global_store_dwordx2 v[142:143], v[128:129], off offset:256
	v_fmac_f32_e32 v198, v132, v64
	v_fmac_f32_e32 v160, v133, v65
	v_cvt_pk_bf16_f32 v128, v198, v160
	v_fmac_f32_e32 v199, v134, v66
	v_fmac_f32_e32 v161, v135, v67
	v_cvt_pk_bf16_f32 v129, v199, v161
	global_store_dwordx2 v[142:143], v[128:129], off offset:288
	v_fmac_f32_e32 v200, v124, v76
	v_fmac_f32_e32 v164, v125, v77
	v_cvt_pk_bf16_f32 v124, v200, v164
	v_cvt_pk_bf16_f32 v125, v201, v165
	global_store_dwordx2 v[126:127], v[124:125], off
	v_fmac_f32_e32 v202, v112, v72
	v_fmac_f32_e32 v166, v113, v73
	v_cvt_pk_bf16_f32 v112, v202, v166
	v_fmac_f32_e32 v203, v114, v74
	v_fmac_f32_e32 v167, v115, v75
	v_cvt_pk_bf16_f32 v113, v203, v167
	v_and_b32_e32 v174, 0xffff0000, v174
	v_lshlrev_b32_e32 v210, 16, v176
	v_and_b32_e32 v176, 0xffff0000, v176
	v_lshlrev_b32_e32 v211, 16, v177
	v_and_b32_e32 v177, 0xffff0000, v177
	global_store_dwordx2 v[126:127], v[112:113], off offset:32
	v_fmac_f32_e32 v204, v120, v68
	v_fmac_f32_e32 v168, v121, v69
	v_cvt_pk_bf16_f32 v112, v204, v168
	v_fmac_f32_e32 v205, v122, v70
	v_fmac_f32_e32 v169, v123, v71
	v_cvt_pk_bf16_f32 v113, v205, v169
	v_fmac_f32_e32 v209, v110, v78
	v_fmac_f32_e32 v175, v111, v79
	v_lshl_add_u64 v[110:111], v[172:173], 0, v[140:141]
	v_lshlrev_b32_e32 v212, 16, v178
	v_and_b32_e32 v178, 0xffff0000, v178
	v_lshlrev_b32_e32 v213, 16, v179
	v_and_b32_e32 v179, 0xffff0000, v179
	v_lshlrev_b32_e32 v217, 16, v185
	v_and_b32_e32 v185, 0xffff0000, v185
	global_store_dwordx2 v[126:127], v[112:113], off offset:256
	v_fmac_f32_e32 v206, v116, v64
	v_fmac_f32_e32 v170, v117, v65
	v_cvt_pk_bf16_f32 v112, v206, v170
	v_fmac_f32_e32 v207, v118, v66
	v_fmac_f32_e32 v171, v119, v67
	v_cvt_pk_bf16_f32 v113, v207, v171
	global_store_dwordx2 v[126:127], v[112:113], off offset:288
	v_fmac_f32_e32 v208, v108, v76
	v_fmac_f32_e32 v174, v109, v77
	v_cvt_pk_bf16_f32 v108, v208, v174
	v_cvt_pk_bf16_f32 v109, v209, v175
	global_store_dwordx2 v[110:111], v[108:109], off
	v_fmac_f32_e32 v210, v96, v72
	v_fmac_f32_e32 v176, v97, v73
	v_cvt_pk_bf16_f32 v96, v210, v176
	v_fmac_f32_e32 v211, v98, v74
	v_fmac_f32_e32 v177, v99, v75
	v_cvt_pk_bf16_f32 v97, v211, v177
	v_lshlrev_b32_e32 v214, 16, v182
	v_and_b32_e32 v182, 0xffff0000, v182
	v_lshlrev_b32_e32 v215, 16, v183
	v_and_b32_e32 v183, 0xffff0000, v183
	v_lshlrev_b32_e32 v216, 16, v184
	v_and_b32_e32 v184, 0xffff0000, v184
	v_lshlrev_b32_e32 v218, 16, v186
	v_and_b32_e32 v186, 0xffff0000, v186
	global_store_dwordx2 v[110:111], v[96:97], off offset:32
	v_fmac_f32_e32 v212, v104, v68
	v_fmac_f32_e32 v178, v105, v69
	v_cvt_pk_bf16_f32 v96, v212, v178
	v_fmac_f32_e32 v213, v106, v70
	v_fmac_f32_e32 v179, v107, v71
	v_cvt_pk_bf16_f32 v97, v213, v179
	v_fmac_f32_e32 v217, v94, v78
	v_fmac_f32_e32 v185, v95, v79
	v_lshl_add_u64 v[94:95], v[148:149], 0, v[140:141]
	v_lshlrev_b32_e32 v219, 16, v187
	v_and_b32_e32 v187, 0xffff0000, v187
	v_lshlrev_b32_e32 v220, 16, v188
	v_and_b32_e32 v188, 0xffff0000, v188
	global_store_dwordx2 v[110:111], v[96:97], off offset:256
	v_fmac_f32_e32 v214, v100, v64
	v_fmac_f32_e32 v182, v101, v65
	v_cvt_pk_bf16_f32 v96, v214, v182
	v_fmac_f32_e32 v215, v102, v66
	v_fmac_f32_e32 v183, v103, v67
	v_cvt_pk_bf16_f32 v97, v215, v183
	global_store_dwordx2 v[110:111], v[96:97], off offset:288
	v_fmac_f32_e32 v216, v92, v76
	v_fmac_f32_e32 v184, v93, v77
	v_cvt_pk_bf16_f32 v92, v216, v184
	v_cvt_pk_bf16_f32 v93, v217, v185
	global_store_dwordx2 v[94:95], v[92:93], off
	v_fmac_f32_e32 v218, v80, v72
	v_fmac_f32_e32 v186, v81, v73
	v_cvt_pk_bf16_f32 v80, v218, v186
	v_lshlrev_b32_e32 v221, 16, v189
	v_and_b32_e32 v189, 0xffff0000, v189
	v_lshlrev_b32_e32 v222, 16, v190
	v_and_b32_e32 v190, 0xffff0000, v190
	v_fmac_f32_e32 v219, v82, v74
	v_fmac_f32_e32 v187, v83, v75
	v_cvt_pk_bf16_f32 v81, v219, v187
	global_store_dwordx2 v[94:95], v[80:81], off offset:32
	v_fmac_f32_e32 v220, v88, v68
	v_fmac_f32_e32 v188, v89, v69
	v_cvt_pk_bf16_f32 v80, v220, v188
	v_lshlrev_b32_e32 v223, 16, v191
	v_and_b32_e32 v191, 0xffff0000, v191
	v_fmac_f32_e32 v221, v90, v70
	v_fmac_f32_e32 v189, v91, v71
	v_cvt_pk_bf16_f32 v81, v221, v189
	global_store_dwordx2 v[94:95], v[80:81], off offset:256
	v_fmac_f32_e32 v222, v84, v64
	v_fmac_f32_e32 v190, v85, v65
	v_cvt_pk_bf16_f32 v80, v222, v190
	v_fmac_f32_e32 v223, v86, v66
	v_fmac_f32_e32 v191, v87, v67
	v_cvt_pk_bf16_f32 v81, v223, v191
	global_store_dwordx2 v[94:95], v[80:81], off offset:288
	v_add_u32_e32 v80, 0x80, v146
	v_ashrrev_i32_e32 v81, 31, v80
	v_add_u32_e32 v90, 0x90, v146
	v_lshlrev_b64 v[80:81], 13, v[80:81]
	v_ashrrev_i32_e32 v91, 31, v90
	v_add_u32_e32 v100, 0xa0, v146
	v_lshl_add_u64 v[80:81], s[50:51], 0, v[80:81]
	v_lshlrev_b64 v[90:91], 13, v[90:91]
	v_ashrrev_i32_e32 v101, 31, v100
	v_add_u32_e32 v110, 0xb0, v146
	v_lshl_add_u64 v[82:83], v[80:81], 0, s[16:17]
	v_lshl_add_u64 v[90:91], s[50:51], 0, v[90:91]
	v_lshlrev_b64 v[100:101], 13, v[100:101]
	v_ashrrev_i32_e32 v111, 31, v110
	v_lshl_add_u64 v[82:83], v[82:83], 0, s[0:1]
	v_lshl_add_u64 v[92:93], v[90:91], 0, s[16:17]
	v_lshl_add_u64 v[100:101], s[50:51], 0, v[100:101]
	v_lshlrev_b64 v[110:111], 13, v[110:111]
	v_lshl_add_u64 v[82:83], v[82:83], 0, v[144:145]
	v_lshl_add_u64 v[92:93], v[92:93], 0, s[0:1]
	v_lshl_add_u64 v[102:103], v[100:101], 0, s[16:17]
	v_lshl_add_u64 v[110:111], s[50:51], 0, v[110:111]
	global_load_dwordx2 v[84:85], v[82:83], off nt
	global_load_dwordx2 v[86:87], v[82:83], off offset:32 nt
	global_load_dwordx2 v[88:89], v[82:83], off offset:256 nt
	s_nop 0
	global_load_dwordx2 v[82:83], v[82:83], off offset:288 nt
	v_lshl_add_u64 v[92:93], v[92:93], 0, v[144:145]
	v_lshl_add_u64 v[102:103], v[102:103], 0, s[0:1]
	v_lshl_add_u64 v[112:113], v[110:111], 0, s[16:17]
	global_load_dwordx2 v[94:95], v[92:93], off nt
	global_load_dwordx2 v[96:97], v[92:93], off offset:32 nt
	global_load_dwordx2 v[98:99], v[92:93], off offset:256 nt
	s_nop 0
	global_load_dwordx2 v[92:93], v[92:93], off offset:288 nt
	v_lshl_add_u64 v[102:103], v[102:103], 0, v[144:145]
	v_lshl_add_u64 v[112:113], v[112:113], 0, s[0:1]
	global_load_dwordx2 v[104:105], v[102:103], off nt
	global_load_dwordx2 v[106:107], v[102:103], off offset:32 nt
	global_load_dwordx2 v[108:109], v[102:103], off offset:256 nt
	s_nop 0
	global_load_dwordx2 v[102:103], v[102:103], off offset:288 nt
	v_lshl_add_u64 v[112:113], v[112:113], 0, v[144:145]
	global_load_dwordx2 v[114:115], v[112:113], off nt
	global_load_dwordx2 v[116:117], v[112:113], off offset:32 nt
	global_load_dwordx2 v[118:119], v[112:113], off offset:256 nt
	s_nop 0
	global_load_dwordx2 v[112:113], v[112:113], off offset:288 nt
	s_waitcnt vmcnt(15)
	v_lshlrev_b32_e32 v121, 16, v85
	v_and_b32_e32 v85, 0xffff0000, v85
	v_lshlrev_b32_e32 v120, 16, v84
	v_and_b32_e32 v84, 0xffff0000, v84
	s_waitcnt vmcnt(14)
	v_lshlrev_b32_e32 v122, 16, v86
	v_and_b32_e32 v86, 0xffff0000, v86
	v_lshlrev_b32_e32 v123, 16, v87
	v_and_b32_e32 v87, 0xffff0000, v87
	s_waitcnt vmcnt(11)
	v_lshlrev_b32_e32 v129, 16, v95
	v_and_b32_e32 v95, 0xffff0000, v95
	v_fmac_f32_e32 v121, v62, v78
	v_fmac_f32_e32 v85, v63, v79
	v_lshl_add_u64 v[62:63], v[80:81], 0, v[140:141]
	v_lshlrev_b32_e32 v124, 16, v88
	v_and_b32_e32 v88, 0xffff0000, v88
	v_lshlrev_b32_e32 v125, 16, v89
	v_and_b32_e32 v89, 0xffff0000, v89
	v_lshlrev_b32_e32 v126, 16, v82
	v_and_b32_e32 v82, 0xffff0000, v82
	v_lshlrev_b32_e32 v127, 16, v83
	v_and_b32_e32 v83, 0xffff0000, v83
	v_lshlrev_b32_e32 v128, 16, v94
	v_and_b32_e32 v94, 0xffff0000, v94
	s_waitcnt vmcnt(10)
	v_lshlrev_b32_e32 v130, 16, v96
	v_and_b32_e32 v96, 0xffff0000, v96
	v_lshlrev_b32_e32 v131, 16, v97
	v_and_b32_e32 v97, 0xffff0000, v97
	s_waitcnt vmcnt(7)
	v_lshlrev_b32_e32 v137, 16, v105
	v_and_b32_e32 v105, 0xffff0000, v105
	v_fmac_f32_e32 v120, v60, v76
	v_fmac_f32_e32 v84, v61, v77
	v_cvt_pk_bf16_f32 v60, v120, v84
	v_cvt_pk_bf16_f32 v61, v121, v85
	global_store_dwordx2 v[62:63], v[60:61], off
	v_fmac_f32_e32 v122, v52, v72
	v_fmac_f32_e32 v86, v53, v73
	v_cvt_pk_bf16_f32 v52, v122, v86
	v_fmac_f32_e32 v123, v54, v74
	v_fmac_f32_e32 v87, v55, v75
	v_cvt_pk_bf16_f32 v53, v123, v87
	v_fmac_f32_e32 v129, v46, v78
	v_fmac_f32_e32 v95, v47, v79
	v_lshl_add_u64 v[46:47], v[90:91], 0, v[140:141]
	v_lshlrev_b32_e32 v132, 16, v98
	v_and_b32_e32 v98, 0xffff0000, v98
	v_lshlrev_b32_e32 v133, 16, v99
	v_and_b32_e32 v99, 0xffff0000, v99
	v_lshlrev_b32_e32 v134, 16, v92
	v_and_b32_e32 v92, 0xffff0000, v92
	v_lshlrev_b32_e32 v135, 16, v93
	v_and_b32_e32 v93, 0xffff0000, v93
	v_lshlrev_b32_e32 v136, 16, v104
	v_and_b32_e32 v104, 0xffff0000, v104
	s_waitcnt vmcnt(7)
	v_lshlrev_b32_e32 v138, 16, v106
	v_and_b32_e32 v106, 0xffff0000, v106
	v_lshlrev_b32_e32 v139, 16, v107
	v_and_b32_e32 v107, 0xffff0000, v107
	s_waitcnt vmcnt(4)
	v_lshlrev_b32_e32 v148, 16, v115
	v_and_b32_e32 v115, 0xffff0000, v115
	global_store_dwordx2 v[62:63], v[52:53], off offset:32
	v_fmac_f32_e32 v124, v56, v68
	v_fmac_f32_e32 v88, v57, v69
	v_cvt_pk_bf16_f32 v52, v124, v88
	v_fmac_f32_e32 v125, v58, v70
	v_fmac_f32_e32 v89, v59, v71
	v_cvt_pk_bf16_f32 v53, v125, v89
	global_store_dwordx2 v[62:63], v[52:53], off offset:256
	v_fmac_f32_e32 v126, v48, v64
	v_fmac_f32_e32 v82, v49, v65
	v_cvt_pk_bf16_f32 v48, v126, v82
	v_fmac_f32_e32 v127, v50, v66
	v_fmac_f32_e32 v83, v51, v67
	v_cvt_pk_bf16_f32 v49, v127, v83
	global_store_dwordx2 v[62:63], v[48:49], off offset:288
	v_fmac_f32_e32 v128, v44, v76
	v_fmac_f32_e32 v94, v45, v77
	v_cvt_pk_bf16_f32 v44, v128, v94
	v_cvt_pk_bf16_f32 v45, v129, v95
	global_store_dwordx2 v[46:47], v[44:45], off
	v_fmac_f32_e32 v130, v36, v72
	v_fmac_f32_e32 v96, v37, v73
	v_cvt_pk_bf16_f32 v36, v130, v96
	v_fmac_f32_e32 v131, v38, v74
	v_fmac_f32_e32 v97, v39, v75
	v_cvt_pk_bf16_f32 v37, v131, v97
	v_fmac_f32_e32 v137, v30, v78
	v_fmac_f32_e32 v105, v31, v79
	v_lshl_add_u64 v[30:31], v[100:101], 0, v[140:141]
	v_lshlrev_b32_e32 v142, 16, v108
	v_and_b32_e32 v108, 0xffff0000, v108
	v_lshlrev_b32_e32 v143, 16, v109
	v_and_b32_e32 v109, 0xffff0000, v109
	v_lshlrev_b32_e32 v144, 16, v102
	v_and_b32_e32 v102, 0xffff0000, v102
	v_lshlrev_b32_e32 v146, 16, v103
	v_and_b32_e32 v103, 0xffff0000, v103
	v_lshlrev_b32_e32 v147, 16, v114
	v_and_b32_e32 v114, 0xffff0000, v114
	s_waitcnt vmcnt(7)
	v_lshlrev_b32_e32 v149, 16, v116
	v_and_b32_e32 v116, 0xffff0000, v116
	v_lshlrev_b32_e32 v151, 16, v117
	v_and_b32_e32 v117, 0xffff0000, v117
	global_store_dwordx2 v[46:47], v[36:37], off offset:32
	v_fmac_f32_e32 v132, v40, v68
	v_fmac_f32_e32 v98, v41, v69
	v_cvt_pk_bf16_f32 v36, v132, v98
	v_fmac_f32_e32 v133, v42, v70
	v_fmac_f32_e32 v99, v43, v71
	v_cvt_pk_bf16_f32 v37, v133, v99
	global_store_dwordx2 v[46:47], v[36:37], off offset:256
	v_fmac_f32_e32 v134, v32, v64
	v_fmac_f32_e32 v92, v33, v65
	v_cvt_pk_bf16_f32 v32, v134, v92
	v_fmac_f32_e32 v135, v34, v66
	v_fmac_f32_e32 v93, v35, v67
	v_cvt_pk_bf16_f32 v33, v135, v93
	global_store_dwordx2 v[46:47], v[32:33], off offset:288
	v_fmac_f32_e32 v136, v28, v76
	v_fmac_f32_e32 v104, v29, v77
	v_cvt_pk_bf16_f32 v28, v136, v104
	v_cvt_pk_bf16_f32 v29, v137, v105
	global_store_dwordx2 v[30:31], v[28:29], off
	v_fmac_f32_e32 v138, v20, v72
	v_fmac_f32_e32 v106, v21, v73
	v_cvt_pk_bf16_f32 v20, v138, v106
	v_fmac_f32_e32 v139, v22, v74
	v_fmac_f32_e32 v107, v23, v75
	v_cvt_pk_bf16_f32 v21, v139, v107
	v_fmac_f32_e32 v148, v14, v78
	v_fmac_f32_e32 v115, v15, v79
	v_lshl_add_u64 v[14:15], v[110:111], 0, v[140:141]
	s_waitcnt vmcnt(10)
	v_lshlrev_b32_e32 v152, 16, v118
	v_and_b32_e32 v118, 0xffff0000, v118
	v_lshlrev_b32_e32 v153, 16, v119
	v_and_b32_e32 v119, 0xffff0000, v119
	s_waitcnt vmcnt(9)
	v_lshlrev_b32_e32 v154, 16, v112
	v_and_b32_e32 v112, 0xffff0000, v112
	v_lshlrev_b32_e32 v155, 16, v113
	v_and_b32_e32 v113, 0xffff0000, v113
	global_store_dwordx2 v[30:31], v[20:21], off offset:32
	v_fmac_f32_e32 v142, v24, v68
	v_fmac_f32_e32 v108, v25, v69
	v_cvt_pk_bf16_f32 v20, v142, v108
	v_fmac_f32_e32 v143, v26, v70
	v_fmac_f32_e32 v109, v27, v71
	v_cvt_pk_bf16_f32 v21, v143, v109
	global_store_dwordx2 v[30:31], v[20:21], off offset:256
	v_fmac_f32_e32 v144, v16, v64
	v_fmac_f32_e32 v102, v17, v65
	v_cvt_pk_bf16_f32 v16, v144, v102
	v_fmac_f32_e32 v146, v18, v66
	v_fmac_f32_e32 v103, v19, v67
	v_cvt_pk_bf16_f32 v17, v146, v103
	global_store_dwordx2 v[30:31], v[16:17], off offset:288
	v_fmac_f32_e32 v147, v12, v76
	v_fmac_f32_e32 v114, v13, v77
	v_cvt_pk_bf16_f32 v12, v147, v114
	v_cvt_pk_bf16_f32 v13, v148, v115
	global_store_dwordx2 v[14:15], v[12:13], off
	v_fmac_f32_e32 v149, v4, v72
	v_fmac_f32_e32 v116, v5, v73
	v_cvt_pk_bf16_f32 v4, v149, v116
	v_fmac_f32_e32 v151, v6, v74
	v_fmac_f32_e32 v117, v7, v75
	v_cvt_pk_bf16_f32 v5, v151, v117
	global_store_dwordx2 v[14:15], v[4:5], off offset:32
	v_fmac_f32_e32 v152, v8, v68
	v_fmac_f32_e32 v118, v9, v69
	v_cvt_pk_bf16_f32 v4, v152, v118
	v_fmac_f32_e32 v153, v10, v70
	v_fmac_f32_e32 v119, v11, v71
	v_cvt_pk_bf16_f32 v5, v153, v119
	global_store_dwordx2 v[14:15], v[4:5], off offset:256
	v_fmac_f32_e32 v154, v0, v64
	v_fmac_f32_e32 v112, v1, v65
	v_cvt_pk_bf16_f32 v0, v154, v112
	v_fmac_f32_e32 v155, v2, v66
	v_fmac_f32_e32 v113, v3, v67
	v_cvt_pk_bf16_f32 v1, v155, v113
	global_store_dwordx2 v[14:15], v[0:1], off offset:288
	s_barrier
	s_cbranch_scc0 .LBB0_1526

.LBB0_1581:
	v_add_u32_e32 v106, s4, v179
	v_ashrrev_i32_e32 v107, 31, v106
	v_lshlrev_b64 v[108:109], 13, v[106:107]
	v_lshl_add_u64 v[132:133], v[66:67], 0, v[108:109]
	global_load_dwordx4 v[0:3], v[68:69], off offset:16
	global_load_dwordx4 v[4:7], v[68:69], off
	global_load_dwordx4 v[8:11], v[68:69], off offset:2064
	global_load_dwordx4 v[12:15], v[68:69], off offset:2048
	global_load_dwordx4 v[16:19], v[70:71], off offset:16
	global_load_dwordx4 v[20:23], v[70:71], off
	global_load_dwordx4 v[24:27], v[72:73], off offset:16
	global_load_dwordx4 v[28:31], v[72:73], off
	global_load_dwordx4 v[32:35], v[74:75], off offset:16
	global_load_dwordx4 v[36:39], v[74:75], off
	global_load_dwordx4 v[40:43], v[76:77], off offset:16
	global_load_dwordx4 v[44:47], v[76:77], off
	global_load_dwordx4 v[48:51], v[78:79], off offset:16
	global_load_dwordx4 v[52:55], v[78:79], off
	global_load_dwordx4 v[56:59], v[80:81], off offset:16
	global_load_dwordx4 v[60:63], v[80:81], off
	global_load_dwordx4 v[136:139], v[132:133], off nt
	global_load_dwordx4 v[144:147], v[132:133], off offset:1024 nt
	global_load_dwordx4 v[152:155], v[132:133], off offset:2048 nt
	global_load_dwordx4 v[160:163], v[132:133], off offset:3072 nt
	v_add_co_u32_e32 v132, vcc, s2, v132
	v_lshlrev_b64 v[106:107], 14, v[106:107]
	s_nop 0
	v_addc_co_u32_e32 v133, vcc, 0, v133, vcc
	global_load_dwordx4 v[182:185], v[132:133], off nt
	global_load_dwordx4 v[186:189], v[132:133], off offset:1024 nt
	global_load_dwordx4 v[190:193], v[132:133], off offset:2048 nt
	global_load_dwordx4 v[194:197], v[132:133], off offset:3072 nt
	v_mov_b32_e32 v83, v65
	v_mov_b32_e32 v85, v65
	v_lshl_add_u64 v[130:131], s[54:55], 0, v[106:107]
	v_mov_b32_e32 v87, v65
	v_lshl_add_u64 v[108:109], v[130:131], 0, v[82:83]
	v_lshl_add_u64 v[110:111], v[130:131], 0, v[84:85]
	v_lshl_add_u64 v[112:113], v[130:131], 0, v[86:87]
	s_add_i32 s4, s4, 1
	s_cmp_eq_u32 s4, 4
	v_lshl_add_u64 v[106:107], v[130:131], 0, v[64:65]
	v_lshl_add_u64 v[114:115], v[130:131], 0, v[88:89]
	v_lshl_add_u64 v[116:117], v[130:131], 0, v[90:91]
	v_lshl_add_u64 v[118:119], v[130:131], 0, v[92:93]
	v_lshl_add_u64 v[120:121], v[130:131], 0, v[94:95]
	v_lshl_add_u64 v[122:123], v[130:131], 0, v[96:97]
	v_lshl_add_u64 v[124:125], v[130:131], 0, v[98:99]
	v_lshl_add_u64 v[126:127], v[130:131], 0, v[100:101]
	v_lshl_add_u64 v[128:129], v[130:131], 0, v[102:103]
	v_lshl_add_u64 v[130:131], v[130:131], 0, v[104:105]
	s_waitcnt vmcnt(0)
	v_lshlrev_b32_e32 v132, 16, v136
	v_and_b32_e32 v133, 0xffff0000, v136
	v_lshlrev_b32_e32 v134, 16, v137
	v_and_b32_e32 v135, 0xffff0000, v137
	v_lshlrev_b32_e32 v136, 16, v138
	v_and_b32_e32 v137, 0xffff0000, v138
	v_lshlrev_b32_e32 v138, 16, v139
	v_and_b32_e32 v139, 0xffff0000, v139
	v_lshlrev_b32_e32 v140, 16, v144
	v_and_b32_e32 v141, 0xffff0000, v144
	v_pk_mul_f32 v[198:199], v[132:133], v[132:133]
	v_pk_mul_f32 v[202:203], v[136:137], v[136:137]
	v_lshlrev_b32_e32 v142, 16, v145
	v_and_b32_e32 v143, 0xffff0000, v145
	v_lshlrev_b32_e32 v144, 16, v146
	v_and_b32_e32 v145, 0xffff0000, v146
	v_pk_mul_f32 v[200:201], v[134:135], v[134:135]
	v_pk_mul_f32 v[204:205], v[138:139], v[138:139]
	v_pk_mul_f32 v[206:207], v[140:141], v[140:141]
	v_add_f32_e32 v83, v202, v203
	v_add_f32_e32 v85, v198, v199
	v_lshlrev_b32_e32 v146, 16, v147
	v_and_b32_e32 v147, 0xffff0000, v147
	v_lshlrev_b32_e32 v148, 16, v152
	v_and_b32_e32 v149, 0xffff0000, v152
	v_pk_mul_f32 v[208:209], v[142:143], v[142:143]
	v_pk_mul_f32 v[210:211], v[144:145], v[144:145]
	v_add_f32_e32 v87, v206, v207
	v_add_f32_e32 v83, v83, v204
	v_add_f32_e32 v85, v85, v200
	v_lshlrev_b32_e32 v150, 16, v153
	v_and_b32_e32 v151, 0xffff0000, v153
	v_lshlrev_b32_e32 v152, 16, v154
	v_and_b32_e32 v153, 0xffff0000, v154
	v_pk_mul_f32 v[212:213], v[146:147], v[146:147]
	v_pk_mul_f32 v[214:215], v[148:149], v[148:149]
	v_lshlrev_b32_e32 v234, 16, v186
	v_and_b32_e32 v235, 0xffff0000, v186
	v_add_f32_e32 v181, v210, v211
	v_add_f32_e32 v83, v205, v83
	v_add_f32_e32 v85, v201, v85
	v_add_f32_e32 v87, v87, v208
	v_lshlrev_b32_e32 v154, 16, v155
	v_and_b32_e32 v155, 0xffff0000, v155
	v_lshlrev_b32_e32 v156, 16, v160
	v_and_b32_e32 v157, 0xffff0000, v160
	v_pk_mul_f32 v[216:217], v[150:151], v[150:151]
	v_pk_mul_f32 v[218:219], v[152:153], v[152:153]
	v_add_f32_e32 v246, v214, v215
	v_pk_mul_f32 v[214:215], v[234:235], v[234:235]
	v_add_f32_e32 v87, v209, v87
	v_add_f32_e32 v181, v181, v212
	v_add_f32_e32 v83, v85, v83
	v_lshlrev_b32_e32 v158, 16, v161
	v_and_b32_e32 v159, 0xffff0000, v161
	v_lshlrev_b32_e32 v160, 16, v162
	v_and_b32_e32 v161, 0xffff0000, v162
	v_pk_mul_f32 v[220:221], v[154:155], v[154:155]
	v_pk_mul_f32 v[222:223], v[156:157], v[156:157]
	v_add_f32_e32 v247, v218, v219
	v_add_f32_e32 v252, v214, v215
	v_add_f32_e32 v181, v213, v181
	v_add_f32_e32 v214, v246, v216
	v_add_f32_e32 v83, v83, v87
	v_lshlrev_b32_e32 v162, 16, v163
	v_and_b32_e32 v163, 0xffff0000, v163
	v_pk_mul_f32 v[224:225], v[158:159], v[158:159]
	v_pk_mul_f32 v[226:227], v[160:161], v[160:161]
	v_lshlrev_b32_e32 v230, 16, v182
	v_and_b32_e32 v231, 0xffff0000, v182
	v_lshlrev_b32_e32 v232, 16, v184
	v_and_b32_e32 v233, 0xffff0000, v184
	v_add_f32_e32 v248, v222, v223
	v_add_f32_e32 v246, v217, v214
	v_add_f32_e32 v216, v247, v220
	v_add_f32_e32 v83, v83, v181
	v_pk_mul_f32 v[228:229], v[162:163], v[162:163]
	v_lshlrev_b32_e32 v182, 16, v183
	v_and_b32_e32 v183, 0xffff0000, v183
	v_lshlrev_b32_e32 v236, 16, v188
	v_and_b32_e32 v237, 0xffff0000, v188
	v_and_b32_e32 v239, 0xffff0000, v190
	v_and_b32_e32 v241, 0xffff0000, v192
	v_and_b32_e32 v243, 0xffff0000, v194
	v_and_b32_e32 v245, 0xffff0000, v196
	v_add_f32_e32 v249, v226, v227
	v_pk_mul_f32 v[198:199], v[230:231], v[230:231]
	v_pk_mul_f32 v[206:207], v[232:233], v[232:233]
	v_add_f32_e32 v220, v221, v216
	v_add_f32_e32 v221, v248, v224
	v_add_f32_e32 v83, v83, v246
	v_lshlrev_b32_e32 v184, 16, v185
	v_and_b32_e32 v185, 0xffff0000, v185
	v_lshlrev_b32_e32 v238, 16, v190
	v_lshlrev_b32_e32 v240, 16, v192
	v_lshlrev_b32_e32 v242, 16, v194
	v_lshlrev_b32_e32 v244, 16, v196
	v_pk_mul_f32 v[202:203], v[182:183], v[182:183]
	v_pk_mul_f32 v[222:223], v[236:237], v[236:237]
	v_add_f32_e32 v250, v198, v199
	v_add_f32_e32 v251, v206, v207
	v_mov_b32_e32 v206, v239
	v_mov_b32_e32 v207, v241
	v_mov_b32_e32 v212, v243
	v_mov_b32_e32 v213, v245
	v_add_f32_e32 v224, v249, v228
	v_add_f32_e32 v221, v225, v221
	v_add_f32_e32 v83, v83, v220
	v_lshlrev_b32_e32 v186, 16, v187
	v_and_b32_e32 v187, 0xffff0000, v187
	v_pk_mul_f32 v[210:211], v[184:185], v[184:185]
	v_mov_b32_e32 v198, v238
	v_mov_b32_e32 v199, v240
	v_mov_b32_e32 v208, v242
	v_mov_b32_e32 v209, v244
	v_add_f32_e32 v222, v222, v223
	v_pk_mul_f32 v[206:207], v[206:207], v[206:207]
	v_pk_mul_f32 v[212:213], v[212:213], v[212:213]
	v_add_f32_e32 v223, v229, v224
	v_add_f32_e32 v202, v250, v202
	v_add_f32_e32 v83, v83, v221
	v_lshlrev_b32_e32 v188, 16, v189
	v_and_b32_e32 v189, 0xffff0000, v189
	v_pk_mul_f32 v[218:219], v[186:187], v[186:187]
	v_pk_fma_f32 v[198:199], v[198:199], v[198:199], v[206:207]
	v_pk_fma_f32 v[206:207], v[208:209], v[208:209], v[212:213]
	v_add_f32_e32 v208, v251, v210
	v_add_f32_e32 v85, v203, v202
	v_add_f32_e32 v83, v83, v223
	v_lshlrev_b32_e32 v190, 16, v191
	v_lshlrev_b32_e32 v192, 16, v193
	v_lshlrev_b32_e32 v194, 16, v195
	v_lshlrev_b32_e32 v196, 16, v197
	v_pk_mul_f32 v[226:227], v[188:189], v[188:189]
	v_add_f32_e32 v209, v252, v218
	v_add_f32_e32 v202, v211, v208
	v_add_f32_e32 v83, v83, v85
	v_and_b32_e32 v191, 0xffff0000, v191
	v_and_b32_e32 v193, 0xffff0000, v193
	v_mov_b32_e32 v204, v190
	v_mov_b32_e32 v205, v192
	v_mov_b32_e32 v214, v194
	v_mov_b32_e32 v215, v196
	v_add_f32_e32 v210, v222, v226
	v_add_f32_e32 v203, v219, v209
	v_add_f32_e32 v83, v83, v202
	v_mov_b32_e32 v200, v191
	v_mov_b32_e32 v201, v193
	v_pk_fma_f32 v[198:199], v[204:205], v[204:205], v[198:199]
	v_pk_fma_f32 v[204:205], v[214:215], v[214:215], v[206:207]
	v_add_f32_e32 v206, v227, v210
	v_add_f32_e32 v83, v83, v203
	v_and_b32_e32 v195, 0xffff0000, v195
	v_and_b32_e32 v197, 0xffff0000, v197
	v_pk_fma_f32 v[198:199], v[200:201], v[200:201], v[198:199]
	v_add_f32_e32 v83, v83, v206
	v_mov_b32_e32 v216, v195
	v_mov_b32_e32 v217, v197
	v_add_f32_e32 v83, v83, v198
	v_pk_fma_f32 v[200:201], v[216:217], v[216:217], v[204:205]
	v_add_f32_e32 v83, v83, v199
	v_add_f32_e32 v83, v83, v200
	v_add_f32_e32 v83, v83, v201
	ds_bpermute_b32 v85, v173, v83
	s_waitcnt lgkmcnt(0)
	v_add_f32_e32 v83, v83, v85
	ds_bpermute_b32 v85, v174, v83
	s_waitcnt lgkmcnt(0)
	v_add_f32_e32 v83, v83, v85
	ds_bpermute_b32 v85, v175, v83
	s_waitcnt lgkmcnt(0)
	v_add_f32_e32 v83, v83, v85
	ds_bpermute_b32 v85, v176, v83
	s_waitcnt lgkmcnt(0)
	v_add_f32_e32 v83, v83, v85
	ds_bpermute_b32 v85, v177, v83
	s_waitcnt lgkmcnt(0)
	v_add_f32_e32 v83, v83, v85
	ds_bpermute_b32 v85, v178, v83
	s_waitcnt lgkmcnt(0)
	v_add_f32_e32 v83, v83, v85
	v_fmamk_f32 v83, v83, 0x39800000, v164
	v_mul_f32_e32 v85, 0x4b800000, v83
	v_cmp_gt_f32_e32 vcc, s3, v83
	s_nop 1
	v_cndmask_b32_e32 v83, v83, v85, vcc
	v_rsq_f32_e32 v83, v83
	s_nop 0
	v_mul_f32_e32 v85, 0x45800000, v83
	v_cndmask_b32_e32 v198, v83, v85, vcc
	v_pk_mul_f32 v[132:133], v[198:199], v[132:133] op_sel_hi:[0,1]
	v_pk_mul_f32 v[134:135], v[198:199], v[134:135] op_sel_hi:[0,1]
	v_pk_mul_f32 v[136:137], v[198:199], v[136:137] op_sel_hi:[0,1]
	v_pk_mul_f32 v[138:139], v[198:199], v[138:139] op_sel_hi:[0,1]
	v_pk_mul_f32 v[140:141], v[198:199], v[140:141] op_sel_hi:[0,1]
	v_pk_mul_f32 v[142:143], v[198:199], v[142:143] op_sel_hi:[0,1]
	v_pk_mul_f32 v[144:145], v[198:199], v[144:145] op_sel_hi:[0,1]
	v_pk_mul_f32 v[146:147], v[198:199], v[146:147] op_sel_hi:[0,1]
	v_pk_mul_f32 v[148:149], v[198:199], v[148:149] op_sel_hi:[0,1]
	v_pk_mul_f32 v[150:151], v[198:199], v[150:151] op_sel_hi:[0,1]
	v_pk_mul_f32 v[152:153], v[198:199], v[152:153] op_sel_hi:[0,1]
	v_pk_mul_f32 v[154:155], v[198:199], v[154:155] op_sel_hi:[0,1]
	v_pk_mul_f32 v[156:157], v[198:199], v[156:157] op_sel_hi:[0,1]
	v_pk_mul_f32 v[158:159], v[198:199], v[158:159] op_sel_hi:[0,1]
	v_pk_mul_f32 v[160:161], v[198:199], v[160:161] op_sel_hi:[0,1]
	v_pk_mul_f32 v[162:163], v[198:199], v[162:163] op_sel_hi:[0,1]
	v_pk_mul_f32 v[200:201], v[198:199], v[230:231] op_sel_hi:[0,1]
	v_pk_mul_f32 v[182:183], v[198:199], v[182:183] op_sel_hi:[0,1]
	v_pk_mul_f32 v[202:203], v[198:199], v[232:233] op_sel_hi:[0,1]
	v_pk_mul_f32 v[184:185], v[198:199], v[184:185] op_sel_hi:[0,1]
	v_pk_mul_f32 v[204:205], v[198:199], v[234:235] op_sel_hi:[0,1]
	v_pk_mul_f32 v[186:187], v[198:199], v[186:187] op_sel_hi:[0,1]
	v_pk_mul_f32 v[206:207], v[198:199], v[236:237] op_sel_hi:[0,1]
	v_pk_mul_f32 v[188:189], v[198:199], v[188:189] op_sel_hi:[0,1]
	v_pk_mul_f32 v[208:209], v[198:199], v[238:239] op_sel_hi:[0,1]
	v_pk_mul_f32 v[190:191], v[198:199], v[190:191] op_sel_hi:[0,1]
	v_pk_mul_f32 v[210:211], v[198:199], v[240:241] op_sel_hi:[0,1]
	v_pk_mul_f32 v[192:193], v[198:199], v[192:193] op_sel_hi:[0,1]
	v_pk_mul_f32 v[212:213], v[198:199], v[242:243] op_sel_hi:[0,1]
	v_pk_mul_f32 v[194:195], v[198:199], v[194:195] op_sel_hi:[0,1]
	v_pk_mul_f32 v[214:215], v[198:199], v[244:245] op_sel_hi:[0,1]
	v_pk_mul_f32 v[196:197], v[198:199], v[196:197] op_sel_hi:[0,1]
	v_pk_mul_f32 v[4:5], v[4:5], v[132:133]
	v_pk_mul_f32 v[6:7], v[6:7], v[134:135]
	v_pk_mul_f32 v[0:1], v[0:1], v[136:137]
	v_pk_mul_f32 v[2:3], v[2:3], v[138:139]
	v_pk_mul_f32 v[12:13], v[12:13], v[140:141]
	v_pk_mul_f32 v[14:15], v[14:15], v[142:143]
	v_pk_mul_f32 v[8:9], v[144:145], v[8:9]
	v_pk_mul_f32 v[10:11], v[146:147], v[10:11]
	v_pk_mul_f32 v[20:21], v[148:149], v[20:21]
	v_pk_mul_f32 v[22:23], v[150:151], v[22:23]
	v_pk_mul_f32 v[16:17], v[152:153], v[16:17]
	v_pk_mul_f32 v[18:19], v[154:155], v[18:19]
	v_pk_mul_f32 v[28:29], v[156:157], v[28:29]
	v_pk_mul_f32 v[30:31], v[158:159], v[30:31]
	v_pk_mul_f32 v[24:25], v[160:161], v[24:25]
	v_pk_mul_f32 v[26:27], v[162:163], v[26:27]
	v_pk_mul_f32 v[36:37], v[200:201], v[36:37]
	v_pk_mul_f32 v[38:39], v[182:183], v[38:39]
	v_pk_mul_f32 v[32:33], v[202:203], v[32:33]
	v_pk_mul_f32 v[34:35], v[184:185], v[34:35]
	v_pk_mul_f32 v[44:45], v[204:205], v[44:45]
	v_pk_mul_f32 v[46:47], v[186:187], v[46:47]
	v_pk_mul_f32 v[40:41], v[206:207], v[40:41]
	v_pk_mul_f32 v[42:43], v[188:189], v[42:43]
	v_pk_mul_f32 v[52:53], v[208:209], v[52:53]
	v_pk_mul_f32 v[54:55], v[190:191], v[54:55]
	v_pk_mul_f32 v[48:49], v[210:211], v[48:49]
	v_pk_mul_f32 v[50:51], v[192:193], v[50:51]
	v_pk_mul_f32 v[60:61], v[212:213], v[60:61]
	v_pk_mul_f32 v[62:63], v[194:195], v[62:63]
	v_pk_mul_f32 v[56:57], v[214:215], v[56:57]
	v_pk_mul_f32 v[58:59], v[196:197], v[58:59]
	global_store_dwordx4 v[106:107], v[4:7], off nt
	global_store_dwordx4 v[106:107], v[0:3], off offset:16 nt
	global_store_dwordx4 v[106:107], v[12:15], off offset:2048 nt
	global_store_dwordx4 v[106:107], v[8:11], off offset:2064 nt
	global_store_dwordx4 v[108:109], v[20:23], off nt
	global_store_dwordx4 v[110:111], v[16:19], off nt
	global_store_dwordx4 v[112:113], v[28:31], off nt
	global_store_dwordx4 v[114:115], v[24:27], off nt
	global_store_dwordx4 v[116:117], v[36:39], off nt
	global_store_dwordx4 v[118:119], v[32:35], off nt
	global_store_dwordx4 v[120:121], v[44:47], off nt
	global_store_dwordx4 v[122:123], v[40:43], off nt
	global_store_dwordx4 v[124:125], v[52:55], off nt
	global_store_dwordx4 v[126:127], v[48:51], off nt
	global_store_dwordx4 v[128:129], v[60:63], off nt
	global_store_dwordx4 v[130:131], v[56:59], off nt
	s_cbranch_scc0 .LBB0_1581
	s_add_i32 s96, s96, s94
	s_add_i32 s0, s0, s1
	s_cmpk_gt_i32 s96, 0xff
	s_cbranch_scc0 .LBB0_1580
